# P4: static priority raise (s_setprio 3) for waves running a compressed-attention/top-16 item, reset at item end
# baseline (speedup 1.0000x reference)
.LBB0_522:
	s_setprio 0
	s_mov_b64 s[0:1], 0

.LBB0_536:
	s_and_b64 vcc, exec, s[0:1]
	s_cbranch_vccz .LBB0_522
	s_setprio 3
	s_lshl_b32 s0, s4, 5
	s_sub_i32 s22, 0xfe0, s0
	v_or_b32_e32 v64, s22, v202
	v_subrev_u32_e32 v0, 31, v64
	v_ashrrev_i32_e32 v163, 4, v0
	v_lshlrev_b64 v[0:1], 8, v[64:65]
	v_lshl_add_u64 v[0:1], v[0:1], 0, s[74:75]
	s_sub_i32 s0, 0xfc0, s0
	v_lshlrev_b64 v[0:1], 1, v[0:1]
	s_lshr_b32 s6, s22, 10
	s_ashr_i32 s7, s0, 4
	v_lshl_add_u64 v[180:181], v[150:151], 0, v[0:1]
	v_lshl_add_u64 v[182:183], v[156:157], 0, v[0:1]
	s_mov_b32 s3, 0
	s_mov_b64 s[4:5], -1
	ds_write2_b32 v203, v65, v65 offset1:2
	ds_write2_b32 v203, v65, v65 offset0:4 offset1:6
	ds_write2_b32 v203, v65, v65 offset0:8 offset1:10
	ds_write2_b32 v203, v65, v65 offset0:12 offset1:14
	ds_write2_b32 v203, v65, v65 offset0:16 offset1:18
	ds_write2_b32 v203, v65, v65 offset0:20 offset1:22
	ds_write2_b32 v203, v65, v65 offset0:24 offset1:26
	ds_write2_b32 v203, v65, v65 offset0:28 offset1:30
	ds_write2_b32 v203, v65, v65 offset0:32 offset1:34
	ds_write2_b32 v203, v65, v65 offset0:36 offset1:38
	ds_write2_b32 v203, v65, v65 offset0:40 offset1:42
	ds_write2_b32 v203, v65, v65 offset0:44 offset1:46
	ds_write2_b32 v203, v65, v65 offset0:48 offset1:50
	ds_write2_b32 v203, v65, v65 offset0:52 offset1:54
	ds_write2_b32 v203, v65, v65 offset0:56 offset1:58
	ds_write2_b32 v203, v65, v65 offset0:60 offset1:62
	s_branch .LBB0_539
